# combined: Xt swizzle + permlane16/32_swap lane reductions in SSD epilogues (no LDS bpermute) + G0 epilogue store-ladder read hoisting
# speedup vs baseline: 1.0049x; 1.0009x over previous
; DI int opaque_tid() { int t = threadIdx.x; asm volatile("" : "+v"(t)); return t; }
; template <int PROBE, int SONLY, int CPS>
; DI void ssd_chunk_loop(const Params& p, int layer, int b, int e, int c0, f32x4 (&h)[8], float& dtot, bool write_final) {
;     ...
;   u32x4 pc[4], pb[4], px[2];
;   u16 pru;
;   {
;     const int nb_ = b * 2048 + c0 * 64;
; #pragma unroll
;     for (int i = 0; i < 4; ++i) {
;       const int idx = tid + 256 * i, r = idx >> 4, c16 = idx & 15;
;       if (!SONLY) pc[i] = *(const u32x4*)(XBC + (size_t)(nb_ + r) * 1280 + 1024 + g * 128 + c16 * 8);
;       pb[i] = *(const u32x4*)(XBC + (size_t)(nb_ + r) * 1280 + 768 + g * 128 + c16 * 8);
;     }
; #pragma unroll
;     for (int i = 0; i < 2; ++i) {
;       const int idx = tid + 256 * i, r = idx >> 3, c8 = idx & 7;
;       px[i] = *(const u32x4*)(XBC + (size_t)(nb_ + r) * 1280 + e * 64 + c8 * 8);
;     }
;     pru = PROJ[(size_t)(nb_ + lane) * NPAD + C_DT + e];
;   }
; template <int PROBE>
; PH void ssd_prompt_item(const Params& p, int layer, int b, int e, int seg) {
;   const int tid = opaque_tid(), lane = tid & 63, w = tid >> 6, quad = lane >> 4, l15 = lane & 15;
;   float* SEND = (float*)(p.ws + WS_SEND) + (size_t)((layer * 96 + b * 12 + e) * NSEG) * 8192;
;   unsigned* SFLAG = (unsigned*)(p.ws + WS_SFLAG) + (layer * 96 + b * 12 + e) * NSEG;
;   f32x4 h[8];
; #pragma unroll
;   for (int i = 0; i < 8; ++i) h[i] = (f32x4){0.f, 0.f, 0.f, 0.f};
;   float dtot = 0.f;
;   const size_t eoff = (size_t)(w * 16 + l15) * 128 + quad * 4;
.LBB0_477:
	s_setprio 3
	s_mul_hi_i32 s0, s84, 0x2aaaaaab
	s_lshr_b32 s1, s0, 31
	s_ashr_i32 s0, s0, 4
	s_add_i32 s86, s0, s1
	s_mul_i32 s0, s86, 0x60
	s_sub_i32 s0, s84, s0
	s_mul_i32 s1, s0, 43
	s_sext_i32_i16 s2, s1
	s_ashr_i32 s2, s2, 9
	s_bfe_u32 s1, s1, 0x1000f
	s_add_i32 s1, s2, s1
	s_sext_i32_i16 s25, s1
	s_mul_i32 s1, s1, 12
	s_sub_i32 s24, s0, s1
	v_readlane_b32 s6, v255, 50
	s_sext_i32_i8 s15, s24
	s_mul_i32 s2, s6, 0x60
	s_add_i32 s2, s2, s15
	s_cmpk_lt_i32 s84, 0xc0
	s_cselect_b64 s[48:49], -1, 0
	s_cmpk_gt_i32 s84, 0xbf
	s_cselect_b64 s[8:9], -1, 0
	v_mov_b32_e32 v174, v182
	s_and_b64 vcc, exec, s[8:9]
	s_mul_i32 s21, s86, 0x280
	s_mul_i32 s19, s86, 10
	s_cbranch_vccnz .LBB0_485
	s_bfe_i32 s0, s24, 0x80000
	s_mul_i32 s0, s0, 43
	s_bfe_u32 s1, s0, 0x1000f
	s_bfe_u32 s0, s0, 0x80008
	s_add_i32 s13, s0, s1
	s_mul_i32 s0, s6, 0xffffffac
	s_add_i32 s0, s2, s0
	s_ashr_i32 s1, s0, 31
	v_readlane_b32 s52, v252, 37
	s_lshl_b64 s[6:7], s[0:1], 2
	v_readlane_b32 s60, v252, 45
	v_readlane_b32 s61, v252, 46
	s_add_u32 s0, s60, s6
	v_readlane_b32 s62, v252, 47
	s_addc_u32 s1, s61, s7
	v_readlane_b32 s63, v252, 48
	s_add_u32 s6, s62, s6
	s_waitcnt vmcnt(2)
	v_mov_b32_e32 v22, v182
	s_addc_u32 s7, s63, s7
	global_load_dword v23, v161, s[6:7]
	global_load_dword v79, v161, s[0:1]
	v_readlane_b32 s50, v254, 18
	s_waitcnt vmcnt(6)
	v_add_u32_e32 v7, 0x100, v22
	s_waitcnt vmcnt(4)
	v_add_u32_e32 v8, 0x200, v22
	v_add_u32_e32 v9, 0x300, v22
	s_sext_i32_i8 s18, s13
	s_lshl_b32 s13, s25, 11
	v_readlane_b32 s51, v254, 19
	v_ashrrev_i32_e32 v73, 4, v22
	v_lshlrev_b32_e32 v6, 4, v22
	v_ashrrev_i32_e32 v75, 4, v7
	v_ashrrev_i32_e32 v76, 4, v8
	v_ashrrev_i32_e32 v77, 4, v9
	s_lshl_b32 s22, s18, 7
	s_lshl_b32 s36, s15, 6
	s_add_i32 s18, s13, s21
	v_mov_b32_e32 v0, s24
	v_mov_b64_e32 v[2:3], s[50:51]
	v_and_b32_e32 v72, 63, v22
	v_and_b32_e32 v160, 0xf0, v6
	s_ashr_i32 s23, s22, 31
	s_ashr_i32 s37, s36, 31
	v_add_u32_e32 v6, s18, v73
	v_add_u32_e32 v8, s18, v75
	v_add_u32_e32 v10, s18, v76
	s_waitcnt vmcnt(2)
	v_add_u32_e32 v12, s18, v77
	v_mov_b64_e32 v[4:5], s[4:5]
	v_bfe_i32 v64, v0, 0, 8
	v_lshlrev_b32_e32 v0, 3, v22
	v_ashrrev_i32_e32 v78, 3, v7
	s_lshl_b64 s[0:1], s[22:23], 1
	s_lshl_b64 s[22:23], s[36:37], 1
	v_or_b32_e32 v13, s18, v72
	v_mad_i64_i32 v[6:7], s[36:37], v6, s34, v[2:3]
	v_mad_i64_i32 v[8:9], s[36:37], v8, s34, v[2:3]
	v_mad_i64_i32 v[10:11], s[36:37], v10, s34, v[2:3]
	v_mad_i64_i32 v[2:3], s[36:37], v12, s34, v[2:3]
	v_ashrrev_i32_e32 v65, 31, v64
	v_and_b32_e32 v33, 56, v0
	s_add_u32 s22, s50, s22
	v_mad_i64_i32 v[4:5], s[36:37], v13, s97, v[4:5]
	v_lshl_add_u64 v[6:7], v[6:7], 0, s[0:1]
	v_lshl_add_u64 v[8:9], v[8:9], 0, s[0:1]
	v_lshl_add_u64 v[10:11], v[10:11], 0, s[0:1]
	v_lshl_add_u64 v[2:3], v[2:3], 0, s[0:1]
	s_waitcnt lgkmcnt(0)
	v_mov_b32_e32 v1, v161
	v_ashrrev_i32_e32 v74, 3, v22
	v_lshlrev_b32_e32 v0, 1, v33
	s_addc_u32 s23, s51, s23
	v_lshl_add_u64 v[16:17], v[64:65], 1, v[4:5]
	v_lshl_add_u64 v[4:5], v[6:7], 0, v[160:161]
	v_lshl_add_u64 v[6:7], v[8:9], 0, v[160:161]
	v_lshl_add_u64 v[8:9], v[10:11], 0, v[160:161]
	v_lshl_add_u64 v[12:13], v[2:3], 0, v[160:161]
	v_add_u32_e32 v18, s18, v74
	v_lshl_add_u64 v[66:67], s[22:23], 0, v[0:1]
	global_load_dwordx4 v[0:3], v[4:5], off offset:1536
	s_nop 0
	global_load_dwordx4 v[4:7], v[6:7], off offset:1536
	s_nop 0
	global_load_dwordx4 v[8:11], v[8:9], off offset:1536
	s_nop 0
	global_load_dwordx4 v[12:15], v[12:13], off offset:1536
	v_add_co_u32_e32 v16, vcc, s16, v16
	v_add_u32_e32 v20, s18, v78
	v_mad_i64_i32 v[18:19], s[22:23], v18, s34, v[66:67]
	v_addc_co_u32_e32 v17, vcc, 0, v17, vcc
	v_mad_i64_i32 v[20:21], s[22:23], v20, s34, v[66:67]
	global_load_dwordx4 v[28:31], v[18:19], off
	global_load_dwordx4 v[24:27], v[20:21], off
	global_load_ushort v95, v[16:17], off offset:1536
	v_ashrrev_i32_e32 v32, 6, v22
	v_and_b32_e32 v16, 48, v22
	v_add_u32_e32 v17, 32, v160
	v_add_u32_e32 v16, 32, v16
	s_mul_i32 s6, s86, 10
	s_add_i32 s18, s6, 10
	s_waitcnt vmcnt(8)
	v_mul_f32_e32 v18, 0x3fb8aa3b, v23
	v_and_b32_e32 v23, 15, v22
	v_lshl_or_b32 v34, v32, 4, v23
	v_mad_u64_u32 v[68:69], s[22:23], v34, s11, v[16:17]
	v_exp_f32_e32 v80, v18
	v_lshlrev_b32_e32 v18, 2, v72
	v_readlane_b32 s22, v255, 27
	s_movk_i32 s36, 0x110
	v_mad_u32_u24 v19, v72, s36, 32
	v_add_u32_e32 v69, s22, v18
	v_lshl_add_u32 v82, v74, 2, s22
	v_lshl_add_u32 v83, v78, 2, s22
	s_movk_i32 s22, 0x1200
	v_mul_i32_i24_e32 v21, 0xfffffef2, v72
	v_mul_lo_u32 v32, v32, s22
	s_add_u32 s0, s50, s0
	v_cmp_gt_u32_e32 vcc, 64, v22
	v_add_u32_e32 v81, s17, v18
	v_and_b32_e32 v20, 0xffffffc0, v22
	v_mul_u32_u24_e32 v18, 0x90, v23
	v_mul_lo_u32 v22, v73, s36
	v_mul_lo_u32 v23, v75, s36
	v_mul_lo_u32 v89, v76, s36
	v_mul_lo_u32 v90, v77, s36
	v_lshl_add_u32 v91, v74, 1, 32
	v_mul_u32_u24_e32 v92, 0x90, v33
	v_lshl_add_u32 v93, v78, 1, 32
	v_add3_u32 v84, v19, v21, v32
	v_lshlrev_b32_e32 v21, 1, v72
	s_addc_u32 s1, s51, s1
	s_mov_b32 s7, 0
	v_cmp_eq_u32_e64 s[36:37], 0, v72
	v_cmp_gt_u32_e64 s[38:39], 2, v72
	v_cmp_gt_u32_e64 s[40:41], 4, v72
	v_cmp_gt_u32_e64 s[42:43], 8, v72
	v_cmp_gt_u32_e64 s[44:45], 16, v72
	v_cmp_gt_u32_e64 s[46:47], 32, v72
	v_add3_u32 v85, 32, v32, v21
	v_lshl_add_u64 v[70:71], s[0:1], 0, v[160:161]
	v_mov_b32_e32 v86, 0
	v_mov_b32_e32 v60, 0
	v_mov_b32_e32 v61, 0
	v_mov_b32_e32 v62, 0
	v_mov_b32_e32 v63, 0
	v_mov_b32_e32 v56, 0
	v_mov_b32_e32 v57, 0
	v_mov_b32_e32 v58, 0
	v_mov_b32_e32 v59, 0
	v_mov_b32_e32 v52, 0
	v_mov_b32_e32 v53, 0
	v_mov_b32_e32 v54, 0
	v_mov_b32_e32 v55, 0
	v_mov_b32_e32 v48, 0
	v_mov_b32_e32 v49, 0
	v_mov_b32_e32 v50, 0
	v_mov_b32_e32 v51, 0
	v_mov_b32_e32 v44, 0
	v_mov_b32_e32 v45, 0
; DI float bf2f(u16 b) { return __uint_as_float(((unsigned)b) << 16); }
; DI float softplus_f(float x) { return x > 20.f ? x : log1pf(__expf(x)); }
; template <int PROBE, int SONLY, int CPS>
; DI void ssd_chunk_loop(const Params& p, int layer, int b, int e, int c0, f32x4 (&h)[8], float& dtot, bool write_final) {
;     ...
;   for (int cc = c0; cc < c0 + CPS; ++cc) {
;     const int base = b * 2048 + cc * 64;
; #pragma unroll
;     for (int i = 0; i < 4; ++i) {
;       const int idx = tid + 256 * i, r = idx >> 4, c16 = idx & 15;
;       if (!SONLY) *(u32x4*)(Cs + r * 136 + c16 * 8) = pc[i];
;       *(u32x4*)(Bs + r * 136 + c16 * 8) = pb[i];
;     }
;     u32x4 xr[2];
;     xr[0] = px[0]; xr[1] = px[1];
;     if (w == 0) {
;       const float dtv = softplus_f(bf2f(pru) + dtb);
;       float a = dtv * ah;
; #pragma unroll
;       for (int d = 1; d < 64; d <<= 1) { const float t = __shfl_up(a, d); if (lane >= d) a += t; }
;       dt_s[lane] = dtv; acs_s[lane] = a;
;     }
; template <int PROBE>
; PH void ssd_prompt_item(const Params& p, int layer, int b, int e, int seg) {
;     ...
;   f32x4 h[8];
; #pragma unroll
;   for (int i = 0; i < 8; ++i) h[i] = (f32x4){0.f, 0.f, 0.f, 0.f};
;   float dtot = 0.f;
;   const size_t eoff = (size_t)(w * 16 + l15) * 128 + quad * 4;
	v_mov_b32_e32 v46, 0
	v_mov_b32_e32 v47, 0
	v_mov_b32_e32 v36, 0
	v_mov_b32_e32 v37, 0
	v_mov_b32_e32 v38, 0
	v_mov_b32_e32 v39, 0
	v_mov_b32_e32 v40, 0
	v_mov_b32_e32 v41, 0
	v_mov_b32_e32 v42, 0
	v_mov_b32_e32 v43, 0
	v_mov_b32_e32 v32, 0
	v_mov_b32_e32 v33, 0
	v_mov_b32_e32 v34, 0
	v_mov_b32_e32 v35, 0
	v_add_u32_e32 v87, v17, v22
	v_add_u32_e32 v88, v17, v23
	v_add_u32_e32 v89, v17, v89
	v_add_u32_e32 v90, v17, v90
	v_add_u32_e32 v91, v91, v92
	v_add_u32_e32 v92, v93, v92
	v_add_u32_e32 v93, v19, v20
	v_add_u32_e32 v94, v16, v18
	v_readlane_b32 s53, v252, 38
	v_readlane_b32 s54, v252, 39
	v_readlane_b32 s55, v252, 40
	v_readlane_b32 s56, v252, 41
	v_readlane_b32 s57, v252, 42
	v_readlane_b32 s58, v252, 43
	v_readlane_b32 s59, v252, 44
	v_readlane_b32 s64, v252, 49
	v_readlane_b32 s65, v252, 50
	v_readlane_b32 s66, v252, 51
	v_readlane_b32 s67, v252, 52
	v_and_b32_e32 v224, 7, v182
	v_lshrrev_b32_e32 v225, 6, v182
	v_and_b32_e32 v230, 3, v224
	v_xor_b32_e32 v226, v225, v230
	v_bfe_u32 v227, v182, 3, 3
	v_lshlrev_b32_e32 v227, 1, v227
	v_mul_u32_u24_e32 v228, 0x480, v224
	v_add3_u32 v227, v227, v228, 32
	v_lshl_add_u32 v91, v226, 4, v227
	v_add_u32_e32 v225, 4, v225
	v_xor_b32_e32 v226, v225, v230
	v_lshl_add_u32 v92, v226, 4, v227
	v_and_b32_e32 v224, 15, v182
	v_lshrrev_b32_e32 v225, 6, v182
	v_lshl_or_b32 v226, v225, 4, v224
	v_lshrrev_b32_e32 v228, 3, v226
	v_and_b32_e32 v228, 3, v228
	v_bfe_u32 v229, v182, 4, 2
	v_xor_b32_e32 v229, v229, v228
	v_mul_u32_u24_e32 v226, 0x90, v226
	v_add_u32_e32 v226, 32, v226
	v_lshl_add_u32 v68, v229, 4, v226
	s_nop 0
	s_nop 0
	s_nop 0
	s_nop 0
	s_nop 0
	s_nop 0
	s_nop 0
	s_nop 0
	s_nop 0
	s_nop 0
	s_nop 0
	s_nop 0
	s_nop 0
	s_nop 0
	s_nop 0
	s_nop 0
.LBB0_479:
	s_waitcnt vmcnt(6)
	ds_write_b128 v87, v[0:3] offset:17408
	s_waitcnt vmcnt(5)
	ds_write_b128 v88, v[4:7] offset:17408
	s_waitcnt vmcnt(4)
	ds_write_b128 v89, v[8:11] offset:17408
	s_waitcnt vmcnt(3)
	ds_write_b128 v90, v[12:15] offset:17408
	s_and_saveexec_b64 s[50:51], vcc
	s_cbranch_execz .LBB0_483
	s_waitcnt vmcnt(0)
	v_lshlrev_b32_e32 v0, 16, v95
	v_add_f32_e32 v0, v79, v0
	s_mov_b32 s0, 0x41a00000
	v_cmp_nlt_f32_e64 s[0:1], s0, v0
	s_and_saveexec_b64 s[52:53], s[0:1]
	s_cbranch_execz .LBB0_482
	v_mul_f32_e32 v0, 0x3fb8aa3b, v0
	v_exp_f32_e32 v14, v0
	s_mov_b32 s0, 0x3f2aaaab
	v_add_f32_e32 v2, 1.0, v14
	v_frexp_mant_f32_e32 v4, v2
	v_cvt_f64_f32_e32 v[0:1], v2
	v_frexp_exp_i32_f64_e32 v0, v[0:1]
	v_cmp_gt_f32_e64 s[0:1], s0, v4
	v_add_f32_e32 v3, -1.0, v2
	v_sub_f32_e32 v5, v3, v2
	v_subbrev_co_u32_e64 v8, s[0:1], 0, v0, s[0:1]
	v_sub_u32_e32 v0, 0, v8
	v_sub_f32_e32 v3, v14, v3
	v_add_f32_e32 v5, 1.0, v5
	v_ldexp_f32 v1, v2, v0
	v_add_f32_e32 v3, v3, v5
	v_add_f32_e32 v2, -1.0, v1
	v_add_f32_e32 v4, 1.0, v1
	v_ldexp_f32 v0, v3, v0
	v_add_f32_e32 v3, 1.0, v2
	v_add_f32_e32 v5, -1.0, v4
	v_sub_f32_e32 v3, v1, v3
	v_sub_f32_e32 v1, v1, v5
	v_add_f32_e32 v3, v0, v3
	v_add_f32_e32 v0, v0, v1
	v_add_f32_e32 v9, v4, v0
	v_rcp_f32_e32 v11, v9
	v_sub_f32_e32 v1, v9, v4
	v_sub_f32_e32 v10, v0, v1
	v_add_f32_e32 v1, v2, v3
	v_mul_f32_e32 v13, v1, v11
	v_sub_f32_e32 v0, v1, v2
	v_mul_f32_e32 v2, v9, v13
	v_fma_f32 v4, v13, v9, -v2
	v_fmac_f32_e32 v4, v13, v10
	v_sub_f32_e32 v12, v3, v0
	v_add_f32_e32 v0, v2, v4
	v_sub_f32_e32 v3, v1, v0
	v_pk_add_f32 v[6:7], v[0:1], v[2:3] neg_lo:[0,1] neg_hi:[0,1]
	v_mov_b32_e32 v5, v0
	v_pk_add_f32 v[0:1], v[6:7], v[4:5] neg_lo:[0,1] neg_hi:[0,1]
	s_mov_b32 s0, 0x3f317218
	v_add_f32_e32 v1, v12, v1
	v_add_f32_e32 v0, v0, v1
	v_add_f32_e32 v1, v3, v0
	v_mul_f32_e32 v12, v11, v1
	v_mul_f32_e32 v2, v9, v12
	v_fma_f32 v4, v12, v9, -v2
	v_fmac_f32_e32 v4, v12, v10
	v_sub_f32_e32 v3, v3, v1
	v_add_f32_e32 v9, v0, v3
	v_add_f32_e32 v0, v2, v4
	v_sub_f32_e32 v3, v1, v0
	v_pk_add_f32 v[6:7], v[0:1], v[2:3] neg_lo:[0,1] neg_hi:[0,1]
	v_mov_b32_e32 v5, v0
	v_pk_add_f32 v[0:1], v[6:7], v[4:5] neg_lo:[0,1] neg_hi:[0,1]
	s_nop 0
	v_add_f32_e32 v1, v9, v1
	v_add_f32_e32 v0, v0, v1
	v_add_f32_e32 v1, v13, v12
	v_add_f32_e32 v0, v3, v0
	v_sub_f32_e32 v2, v1, v13
	v_mul_f32_e32 v0, v11, v0
	v_sub_f32_e32 v2, v12, v2
	v_add_f32_e32 v2, v2, v0
	v_add_f32_e32 v4, v1, v2
	v_mul_f32_e32 v5, v4, v4
	v_fmamk_f32 v0, v5, 0x3e9b6dac, v184
	v_fmaak_f32 v163, v5, v0, 0x3f2aaada
	v_cvt_f32_i32_e32 v0, v8
	v_sub_f32_e32 v1, v4, v1
	v_sub_f32_e32 v1, v2, v1
	v_ldexp_f32 v6, v1, 1
	v_mul_f32_e32 v1, v4, v5
	v_ldexp_f32 v3, v4, 1
	v_pk_mul_f32 v[4:5], v[0:1], v[162:163]
	s_nop 0
	v_fma_f32 v2, v0, s0, -v4
	v_fmac_f32_e32 v2, 0xb102e308, v0
	v_pk_add_f32 v[0:1], v[4:5], v[2:3]
	s_mov_b32 s0, 0x7f800000
	v_sub_f32_e32 v3, v1, v3
	v_sub_f32_e32 v3, v5, v3
	v_add_f32_e32 v7, v6, v3
	v_mov_b32_e32 v6, v4
	v_pk_add_f32 v[4:5], v[0:1], v[4:5] neg_lo:[0,1] neg_hi:[0,1]
	v_pk_add_f32 v[8:9], v[0:1], v[6:7]
	v_mov_b32_e32 v3, v0
	v_mov_b32_e32 v5, v9
	v_pk_add_f32 v[10:11], v[2:3], v[4:5] neg_lo:[0,1] neg_hi:[0,1]
	v_pk_add_f32 v[2:3], v[2:3], v[4:5]
	v_mov_b32_e32 v6, v7
	v_pk_add_f32 v[4:5], v[2:3], v[0:1] op_sel:[1,0] op_sel_hi:[0,1] neg_lo:[0,1] neg_hi:[0,1]
	v_pk_add_f32 v[12:13], v[8:9], v[4:5] op_sel_hi:[1,0] neg_lo:[0,1] neg_hi:[0,1]
	v_mov_b32_e32 v8, v9
	v_mov_b32_e32 v9, v3
	v_pk_mov_b32 v[4:5], v[0:1], v[4:5] op_sel:[1,0]
	v_mov_b32_e32 v7, v0
	v_pk_add_f32 v[4:5], v[8:9], v[4:5] neg_lo:[0,1] neg_hi:[0,1]
	v_mov_b32_e32 v12, v10
	v_pk_add_f32 v[0:1], v[6:7], v[4:5] neg_lo:[0,1] neg_hi:[0,1]
	v_mov_b32_e32 v11, v3
	v_pk_add_f32 v[4:5], v[12:13], v[0:1]
	v_cmp_neq_f32_e64 s[0:1], s0, v14
	v_pk_add_f32 v[6:7], v[4:5], v[4:5] op_sel:[0,1] op_sel_hi:[1,0]
	s_nop 0
	v_pk_add_f32 v[2:3], v[2:3], v[6:7] op_sel:[1,0] op_sel_hi:[0,1]
	v_mov_b32_e32 v5, v2
	v_pk_add_f32 v[8:9], v[4:5], v[10:11] neg_lo:[0,1] neg_hi:[0,1]
	v_mov_b32_e32 v1, v6
	v_sub_f32_e32 v3, v4, v8
	v_pk_add_f32 v[0:1], v[0:1], v[8:9] neg_lo:[0,1] neg_hi:[0,1]
	v_sub_f32_e32 v3, v10, v3
	v_add_f32_e32 v0, v0, v3
	v_add_f32_e32 v0, v0, v1
	v_add_f32_e32 v0, v2, v0
	v_cndmask_b32_e64 v0, v196, v0, s[0:1]
	v_cmp_ngt_f32_e64 s[0:1], -1.0, v14
	s_nop 1
	v_cndmask_b32_e64 v0, v197, v0, s[0:1]
	v_cmp_neq_f32_e64 s[0:1], -1.0, v14
	s_nop 1
	v_cndmask_b32_e64 v0, v191, v0, s[0:1]
	s_mov_b32 s0, 0x33800000
	v_cmp_lt_f32_e64 s[0:1], |v14|, s0
	s_nop 1
	v_cndmask_b32_e64 v0, v0, v14, s[0:1]

; DI f32x4 mfma16(bf16x8 a, bf16x8 b, f32x4 c) { return __builtin_amdgcn_mfma_f32_16x16x32_bf16(a, b, c, 0, 0, 0); }
; template <int PROBE, int SONLY, int CPS>
; DI void ssd_chunk_loop(const Params& p, int layer, int b, int e, int c0, f32x4 (&h)[8], float& dtot, bool write_final) {
;     ...
;         *(uint2*)(Ms + q * 72 + s0) = ov;
;       }
;     }
;     f32x4 y[4];
; #pragma unroll
;     for (int qt = 0; qt < 4; ++qt) y[qt] = (f32x4){0.f, 0.f, 0.f, 0.f};
;     if (!(PROBE & 4) && !SONLY)
; #pragma unroll
;     for (int kk = 0; kk < 4; ++kk) {
;       const bf16x8 hf = packfrag(h[2 * kk], h[2 * kk + 1]);
; #pragma unroll
;       for (int qt = 0; qt < 4; ++qt) y[qt] = mfma16(hf, ldfrag_perm(Cs, 136, qt * 16, kk * 32, lane), y[qt]);
;     }
;     if (!SONLY) {
; #pragma unroll
;     for (int qt = 0; qt < 4; ++qt) y[qt] *= __expf(acs_s[qt * 16 + l15]);
;     __syncthreads();
;     }
;     if (!(PROBE & 8) && !SONLY)
; #pragma unroll
;     for (int qt = 0; qt < 4; ++qt)
; #pragma unroll
;       for (int ks = 0; ks < 2; ++ks)
;         if (ks == 0 || qt >= 2) y[qt] = mfma16(ldfrag(Xt, 72, w * 16, ks * 32, lane), ldfrag(Ms, 72, qt * 16, ks * 32, lane), y[qt]);
;     if (!(PROBE & 8)) {
;       const float cd = __expf(acs_s[63]);
; #pragma unroll
;       for (int nt = 0; nt < 8; ++nt) h[nt] *= cd;
; #pragma unroll
;       for (int ks = 0; ks < 2; ++ks) {
;         const bf16x8 xf = ldfrag(Xt, 72, w * 16, ks * 32, lane);
; #pragma unroll
;         for (int nt = 0; nt < 8; ++nt) h[nt] = mfma16(ldfrag(Bt2, 72, nt * 16, ks * 32, lane), xf, h[nt]);
;       }
.LBB0_543:
	s_or_b64 exec, exec, s[6:7]
	v_cvt_pk_bf16_f32 v106, v120, v108
	v_cvt_pk_bf16_f32 v107, v104, v105
	ds_write_b64 v227, v[106:107] offset:62560
	ds_read2_b64 v[0:3], v245 offset1:4
	v_add_u32_e32 v149, 0x1000, v245
	ds_read2_b64 v[4:7], v149 offset0:32 offset1:36
	v_add_u32_e32 v155, 0x2000, v245
	ds_read2_b64 v[8:11], v155 offset0:64 offset1:68
	v_add_u32_e32 v165, 0x3000, v245
	ds_read2_b64 v[12:15], v165 offset0:96 offset1:100
	ds_read2_b64 v[16:19], v245 offset0:8 offset1:12
	ds_read2_b64 v[20:23], v149 offset0:40 offset1:44
	ds_read2_b64 v[24:27], v155 offset0:72 offset1:76
	ds_read2_b64 v[28:31], v165 offset0:104 offset1:108
	v_cvt_pk_bf16_f32 v104, v64, v65
	v_cvt_pk_bf16_f32 v105, v66, v67
	v_cvt_pk_bf16_f32 v106, v68, v69
	v_cvt_pk_bf16_f32 v107, v70, v71
	s_nop 0
	s_nop 0
	s_nop 0
	s_nop 0
	s_nop 0
	s_waitcnt lgkmcnt(7)
	v_mfma_f32_16x16x32_bf16 v[108:111], v[104:107], v[0:3], 0
	ds_read2_b64 v[0:3], v245 offset0:16 offset1:20
	s_nop 0
	s_nop 0
	s_waitcnt lgkmcnt(7)
	v_mfma_f32_16x16x32_bf16 v[112:115], v[104:107], v[4:7], 0
	ds_read2_b64 v[4:7], v149 offset0:48 offset1:52
	s_nop 0
	s_waitcnt lgkmcnt(7)
	v_mfma_f32_16x16x32_bf16 v[116:119], v[104:107], v[8:11], 0
	ds_read2_b64 v[8:11], v155 offset0:80 offset1:84
	s_nop 0
	s_waitcnt lgkmcnt(7)
	v_mfma_f32_16x16x32_bf16 v[104:107], v[104:107], v[12:15], 0
	ds_read2_b64 v[12:15], v165 offset0:112 offset1:116
	v_cvt_pk_bf16_f32 v120, v72, v73
	v_cvt_pk_bf16_f32 v121, v74, v75
	v_cvt_pk_bf16_f32 v122, v76, v77
	v_cvt_pk_bf16_f32 v123, v78, v79
	s_nop 0
	s_nop 0
	s_waitcnt lgkmcnt(7)
	v_mfma_f32_16x16x32_bf16 v[108:111], v[120:123], v[16:19], v[108:111]
	ds_read2_b64 v[16:19], v245 offset0:24 offset1:28
	s_nop 0
	s_nop 0
	s_waitcnt lgkmcnt(7)
	v_mfma_f32_16x16x32_bf16 v[112:115], v[120:123], v[20:23], v[112:115]
	ds_read2_b64 v[20:23], v149 offset0:56 offset1:60
	s_nop 0
	s_nop 0
	s_waitcnt lgkmcnt(7)
	v_mfma_f32_16x16x32_bf16 v[116:119], v[120:123], v[24:27], v[116:119]
	ds_read2_b64 v[24:27], v155 offset0:88 offset1:92
	s_nop 0
	s_nop 0
	s_waitcnt lgkmcnt(7)
	v_mfma_f32_16x16x32_bf16 v[104:107], v[120:123], v[28:31], v[104:107]
	v_cvt_pk_bf16_f32 v120, v80, v81
	v_cvt_pk_bf16_f32 v121, v82, v83
	v_cvt_pk_bf16_f32 v122, v84, v85
	v_cvt_pk_bf16_f32 v123, v86, v87
	s_nop 0
	s_nop 0
	s_waitcnt lgkmcnt(6)
	v_mfma_f32_16x16x32_bf16 v[108:111], v[120:123], v[0:3], v[108:111]
	s_nop 0
	s_nop 0
	s_waitcnt lgkmcnt(5)
	v_mfma_f32_16x16x32_bf16 v[112:115], v[120:123], v[4:7], v[112:115]
	s_nop 0
	s_nop 0
	s_waitcnt lgkmcnt(4)
	v_mfma_f32_16x16x32_bf16 v[116:119], v[120:123], v[8:11], v[116:119]
	s_nop 0
	s_nop 0
	s_waitcnt lgkmcnt(3)
	v_mfma_f32_16x16x32_bf16 v[104:107], v[120:123], v[12:15], v[104:107]
	v_cvt_pk_bf16_f32 v120, v88, v89
	v_cvt_pk_bf16_f32 v121, v90, v91
	v_cvt_pk_bf16_f32 v122, v92, v93
	v_cvt_pk_bf16_f32 v123, v94, v95
	s_nop 0
	s_nop 0
	s_waitcnt lgkmcnt(2)
	v_mfma_f32_16x16x32_bf16 v[108:111], v[120:123], v[16:19], v[108:111]
	s_nop 0
	v_mov_b32_e32 v149, s20
	s_nop 0
	s_waitcnt lgkmcnt(1)
	v_mfma_f32_16x16x32_bf16 v[112:115], v[120:123], v[20:23], v[112:115]
	s_nop 0
	s_nop 0
	s_waitcnt lgkmcnt(0)
	v_mfma_f32_16x16x32_bf16 v[116:119], v[120:123], v[24:27], v[116:119]
	ds_read2_b64 v[124:127], v165 offset0:120 offset1:124
	s_nop 0
	s_waitcnt lgkmcnt(0)
	v_mfma_f32_16x16x32_bf16 v[104:107], v[120:123], v[124:127], v[104:107]
	ds_read2_b32 v[120:121], v211 offset1:16
	ds_read2_b32 v[122:123], v211 offset0:32 offset1:48
	s_waitcnt lgkmcnt(0)
	s_waitcnt lgkmcnt(0)
	s_barrier
	ds_read_b128 v[0:3], v212 offset:53248
	ds_read_b128 v[4:7], v246 offset:62464
	ds_read_b128 v[8:11], v246 offset:64768
	ds_read_b128 v[12:15], v247 offset:62464
	ds_read_b128 v[16:19], v247 offset:62528
	ds_read_b32 v20, v149
	ds_read_b128 v[24:27], v247 offset:64768
	ds_read_b128 v[28:31], v246 offset:34816
	v_mul_f32_e32 v120, 0x3fb8aa3b, v120
	v_exp_f32_e32 v120, v120
	v_mul_f32_e32 v123, 0x3fb8aa3b, v123
	v_exp_f32_e32 v124, v123
	v_pk_mul_f32 v[110:111], v[110:111], v[120:121] op_sel_hi:[1,0]
	v_pk_mul_f32 v[108:109], v[108:109], v[120:121] op_sel_hi:[1,0]
	v_mul_f32_e32 v120, 0x3fb8aa3b, v121
	v_exp_f32_e32 v120, v120
	v_pk_mul_f32 v[106:107], v[106:107], v[124:125] op_sel_hi:[1,0]
	v_pk_mul_f32 v[104:105], v[104:105], v[124:125] op_sel_hi:[1,0]
	v_pk_mul_f32 v[114:115], v[114:115], v[120:121] op_sel_hi:[1,0]
	v_pk_mul_f32 v[112:113], v[112:113], v[120:121] op_sel_hi:[1,0]
	v_mul_f32_e32 v120, 0x3fb8aa3b, v122
	v_exp_f32_e32 v120, v120
	s_nop 0
	v_pk_mul_f32 v[122:123], v[118:119], v[120:121] op_sel_hi:[1,0]
	v_pk_mul_f32 v[120:121], v[116:117], v[120:121] op_sel_hi:[1,0]
	s_nop 0
	s_nop 0
	s_nop 0
	s_waitcnt lgkmcnt(6)
	v_mfma_f32_16x16x32_bf16 v[116:119], v[0:3], v[4:7], v[108:111]
	ds_read_b128 v[4:7], v246 offset:37120
	s_nop 2
	s_nop 0
	s_nop 0
	s_waitcnt lgkmcnt(6)
	v_mfma_f32_16x16x32_bf16 v[112:115], v[0:3], v[8:11], v[112:115]
	ds_read_b128 v[8:11], v246 offset:39424
	s_nop 0
	s_nop 0
	s_waitcnt lgkmcnt(6)
	v_mfma_f32_16x16x32_bf16 v[108:111], v[0:3], v[12:15], v[120:123]
	ds_read_b128 v[12:15], v246 offset:41728
	s_nop 2
	ds_read_b128 v[120:123], v212 offset:53312
	s_nop 0
	s_nop 0
	s_nop 0
	s_waitcnt lgkmcnt(6)
	v_mul_f32_e32 v149, 0x3fb8aa3b, v20
	ds_read_b128 v[20:23], v246 offset:44032
	s_waitcnt lgkmcnt(1)
	v_mfma_f32_16x16x32_bf16 v[108:111], v[120:123], v[16:19], v[108:111]
	ds_read_b128 v[16:19], v246 offset:46336
	s_nop 0
	s_nop 0
	v_mfma_f32_16x16x32_bf16 v[104:107], v[0:3], v[24:27], v[104:107]
	ds_read_b128 v[24:27], v246 offset:48640
	ds_read_b128 v[248:251], v247 offset:64832
	s_nop 0
	s_waitcnt lgkmcnt(0)
; DI unsigned pack2(float a, float b) { fl2_t v = {a, b}; return __builtin_bit_cast(unsigned, __builtin_convertvector(v, bf2_t)); }
; DI float bflo(unsigned u) { return __uint_as_float(u << 16); }
; DI float bfhi(unsigned u) { return __uint_as_float(u & 0xffff0000u); }
; DI f32x4 mfma16(bf16x8 a, bf16x8 b, f32x4 c) { return __builtin_amdgcn_mfma_f32_16x16x32_bf16(a, b, c, 0, 0, 0); }
; DI float silu_f(float x) { return x * __builtin_amdgcn_rcpf(1.f + __expf(-x)); }
; template <int PROBE, int SONLY, int CPS>
; DI void ssd_chunk_loop(const Params& p, int layer, int b, int e, int c0, f32x4 (&h)[8], float& dtot, bool write_final) {
;     ...
;     if (!(PROBE & 8)) {
;       const float cd = __expf(acs_s[63]);
; #pragma unroll
;       for (int nt = 0; nt < 8; ++nt) h[nt] *= cd;
; #pragma unroll
;       for (int ks = 0; ks < 2; ++ks) {
;         const bf16x8 xf = ldfrag(Xt, 72, w * 16, ks * 32, lane);
; #pragma unroll
;         for (int nt = 0; nt < 8; ++nt) h[nt] = mfma16(ldfrag(Bt2, 72, nt * 16, ks * 32, lane), xf, h[nt]);
;       }
;     }
;     if (!SONLY)
; #pragma unroll
;     for (int qt = 0; qt < 4; ++qt) {
;       const int q = qt * 16 + l15;
;       const size_t row = (size_t)(base + q);
;       const int pcol = w * 16 + quad * 4;
;       const uint2 xv = dx[qt];
;       const uint2 zv = dz[qt];
;       const float y0 = (y[qt][0] + Dv * bflo(xv.x)) * silu_f(bflo(zv.x));
;       const float y1 = (y[qt][1] + Dv * bfhi(xv.x)) * silu_f(bfhi(zv.x));
;       const float y2 = (y[qt][2] + Dv * bflo(xv.y)) * silu_f(bflo(zv.y));
;       const float y3 = (y[qt][3] + Dv * bfhi(xv.y)) * silu_f(bfhi(zv.y));
;       uint2 ov; ov.x = pack2(y0, y1); ov.y = pack2(y2, y3);
;       if (do_store) *(uint2*)(MIX + row * 2048 + 1280 + e * 64 + pcol) = ov;
;       float ss = y0 * y0 + y1 * y1 + y2 * y2 + y3 * y3;
;       ss += __shfl_xor(ss, 16);
;       ss += __shfl_xor(ss, 32);
;       if (quad == 0) ssq_s[w * 64 + q] = ss;
;     }
	v_mfma_f32_16x16x32_bf16 v[104:107], v[120:123], v[248:251], v[104:107]
	v_exp_f32_e32 v248, v149
	s_nop 0
	v_pk_mul_f32 v[66:67], v[66:67], v[248:249] op_sel_hi:[1,0]
	v_pk_mul_f32 v[64:65], v[64:65], v[248:249] op_sel_hi:[1,0]
	v_pk_mul_f32 v[70:71], v[70:71], v[248:249] op_sel_hi:[1,0]
	v_pk_mul_f32 v[68:69], v[68:69], v[248:249] op_sel_hi:[1,0]
	v_pk_mul_f32 v[74:75], v[74:75], v[248:249] op_sel_hi:[1,0]
	v_pk_mul_f32 v[72:73], v[72:73], v[248:249] op_sel_hi:[1,0]
	v_pk_mul_f32 v[78:79], v[78:79], v[248:249] op_sel_hi:[1,0]
	v_pk_mul_f32 v[76:77], v[76:77], v[248:249] op_sel_hi:[1,0]
	v_pk_mul_f32 v[82:83], v[82:83], v[248:249] op_sel_hi:[1,0]
	v_pk_mul_f32 v[80:81], v[80:81], v[248:249] op_sel_hi:[1,0]
	v_pk_mul_f32 v[86:87], v[86:87], v[248:249] op_sel_hi:[1,0]
	v_pk_mul_f32 v[84:85], v[84:85], v[248:249] op_sel_hi:[1,0]
	v_pk_mul_f32 v[90:91], v[90:91], v[248:249] op_sel_hi:[1,0]
	v_pk_mul_f32 v[88:89], v[88:89], v[248:249] op_sel_hi:[1,0]
	v_pk_mul_f32 v[94:95], v[94:95], v[248:249] op_sel_hi:[1,0]
	v_pk_mul_f32 v[92:93], v[92:93], v[248:249] op_sel_hi:[1,0]
	s_nop 0
	s_nop 0
	v_mfma_f32_16x16x32_bf16 v[64:67], v[28:31], v[0:3], v[64:67]
	ds_read_b128 v[28:31], v246 offset:34880
	s_nop 0
	s_nop 0
	v_mfma_f32_16x16x32_bf16 v[68:71], v[4:7], v[0:3], v[68:71]
	ds_read_b128 v[4:7], v246 offset:37184
	s_nop 0
	s_nop 0
	v_mfma_f32_16x16x32_bf16 v[72:75], v[8:11], v[0:3], v[72:75]
	ds_read_b128 v[8:11], v246 offset:39488
	s_nop 0
	s_nop 0
	v_mfma_f32_16x16x32_bf16 v[76:79], v[12:15], v[0:3], v[76:79]
	ds_read_b128 v[12:15], v246 offset:41792
	s_nop 0
	s_nop 0
	v_mfma_f32_16x16x32_bf16 v[80:83], v[20:23], v[0:3], v[80:83]
	ds_read_b128 v[20:23], v246 offset:44096
	s_nop 0
	s_nop 0
	v_mfma_f32_16x16x32_bf16 v[84:87], v[16:19], v[0:3], v[84:87]
	ds_read_b128 v[16:19], v246 offset:46400
	s_nop 0
	s_nop 0
	v_mfma_f32_16x16x32_bf16 v[88:91], v[24:27], v[0:3], v[88:91]
	ds_read_b128 v[24:27], v246 offset:48704
	ds_read_b128 v[248:251], v246 offset:50944
	s_nop 0
	s_waitcnt lgkmcnt(0)
	v_mfma_f32_16x16x32_bf16 v[92:95], v[248:251], v[0:3], v[92:95]
	s_nop 0
	s_nop 0
	v_mfma_f32_16x16x32_bf16 v[64:67], v[28:31], v[120:123], v[64:67]
	s_nop 0
	s_nop 0
	v_mfma_f32_16x16x32_bf16 v[68:71], v[4:7], v[120:123], v[68:71]
	s_nop 0
	s_nop 0
	v_mfma_f32_16x16x32_bf16 v[72:75], v[8:11], v[120:123], v[72:75]
	s_nop 0
	s_nop 0
	v_mfma_f32_16x16x32_bf16 v[76:79], v[12:15], v[120:123], v[76:79]
	s_nop 0
	s_nop 0
	v_mfma_f32_16x16x32_bf16 v[80:83], v[20:23], v[120:123], v[80:83]
	s_nop 0
	s_nop 0
	v_mfma_f32_16x16x32_bf16 v[84:87], v[16:19], v[120:123], v[84:87]
	s_nop 0
	s_nop 0
	v_mfma_f32_16x16x32_bf16 v[88:91], v[24:27], v[120:123], v[88:91]
	ds_read_b128 v[124:127], v246 offset:51008
	s_nop 0
	s_waitcnt lgkmcnt(0)
	v_mfma_f32_16x16x32_bf16 v[92:95], v[124:127], v[120:123], v[92:95]
	s_waitcnt vmcnt(7)
	v_lshlrev_b32_e32 v120, 16, v172
	s_waitcnt vmcnt(6)
	v_lshlrev_b32_e32 v122, 16, v170
	v_and_b32_e32 v121, 0xffff0000, v172
	v_and_b32_e32 v123, 0xffff0000, v170
	v_mul_f32_e32 v124, 0xbfb8aa3b, v122
	v_pk_fma_f32 v[116:117], v[128:129], v[120:121], v[116:117]
	v_mul_f32_e32 v120, 0xbfb8aa3b, v123
	v_exp_f32_e32 v124, v124
	v_exp_f32_e32 v120, v120
	v_add_f32_e32 v124, 1.0, v124
	v_add_f32_e32 v120, 1.0, v120
	v_rcp_f32_e32 v124, v124
	v_rcp_f32_e32 v125, v120
	s_nop 0
	v_pk_mul_f32 v[120:121], v[124:125], v[122:123]
	s_nop 0
	v_pk_mul_f32 v[116:117], v[120:121], v[116:117]
	v_lshlrev_b32_e32 v120, 16, v173
	v_lshlrev_b32_e32 v122, 16, v171
	v_and_b32_e32 v121, 0xffff0000, v173
	v_and_b32_e32 v123, 0xffff0000, v171
	v_mul_f32_e32 v124, 0xbfb8aa3b, v122
	v_pk_fma_f32 v[118:119], v[128:129], v[120:121], v[118:119]
	v_mul_f32_e32 v120, 0xbfb8aa3b, v123
	v_exp_f32_e32 v124, v124
	v_exp_f32_e32 v120, v120
	v_add_f32_e32 v124, 1.0, v124
	v_add_f32_e32 v120, 1.0, v120
	v_rcp_f32_e32 v124, v124
	v_rcp_f32_e32 v125, v120
	s_nop 0
	v_pk_mul_f32 v[120:121], v[124:125], v[122:123]
	s_nop 0
	v_pk_mul_f32 v[118:119], v[120:121], v[118:119]
	v_cvt_pk_bf16_f32 v120, v116, v117
	v_pk_mul_f32 v[116:117], v[116:117], v[116:117]
	v_cvt_pk_bf16_f32 v121, v118, v119
	v_pk_mul_f32 v[118:119], v[118:119], v[118:119]
	v_add_f32_e32 v116, v116, v117
	v_add_f32_e32 v116, v118, v116
	v_add_f32_e32 v116, v119, v116
	v_mov_b32_e32 v117, v116
	s_nop 1
	v_permlane16_swap_b32_e32 v116, v117
	v_lshlrev_b64 v[122:123], 12, v[160:161]
	v_lshl_add_u64 v[122:123], s[94:95], 0, v[122:123]
	v_lshl_add_u64 v[122:123], v[122:123], 0, s[2:3]
	v_lshl_add_u64 v[122:123], v[134:135], 1, v[122:123]
	s_waitcnt lgkmcnt(0)
	v_add_f32_e32 v116, v116, v117
	v_mov_b32_e32 v117, v116
	s_nop 1
	v_permlane32_swap_b32_e32 v116, v117
	v_add_co_u32_e32 v122, vcc, s14, v122
	s_nop 1
	v_addc_co_u32_e32 v123, vcc, 0, v123, vcc
	global_store_dwordx2 v[122:123], v[120:121], off offset:2560
	s_and_saveexec_b64 s[6:7], s[38:39]
	s_cbranch_execz .LBB0_545
	s_waitcnt lgkmcnt(0)
	v_add_f32_e32 v116, v116, v117
	ds_write_b32 v240, v116
; DI unsigned pack2(float a, float b) { fl2_t v = {a, b}; return __builtin_bit_cast(unsigned, __builtin_convertvector(v, bf2_t)); }
; DI float bflo(unsigned u) { return __uint_as_float(u << 16); }
; DI float bfhi(unsigned u) { return __uint_as_float(u & 0xffff0000u); }
; DI float silu_f(float x) { return x * __builtin_amdgcn_rcpf(1.f + __expf(-x)); }
; template <int PROBE, int SONLY, int CPS>
; DI void ssd_chunk_loop(const Params& p, int layer, int b, int e, int c0, f32x4 (&h)[8], float& dtot, bool write_final) {
;     ...
;     for (int qt = 0; qt < 4; ++qt) {
;       const int q = qt * 16 + l15;
;       const size_t row = (size_t)(base + q);
;       const int pcol = w * 16 + quad * 4;
;       const uint2 xv = dx[qt];
;       const uint2 zv = dz[qt];
;       const float y0 = (y[qt][0] + Dv * bflo(xv.x)) * silu_f(bflo(zv.x));
;       const float y1 = (y[qt][1] + Dv * bfhi(xv.x)) * silu_f(bfhi(zv.x));
;       const float y2 = (y[qt][2] + Dv * bflo(xv.y)) * silu_f(bflo(zv.y));
;       const float y3 = (y[qt][3] + Dv * bfhi(xv.y)) * silu_f(bfhi(zv.y));
;       uint2 ov; ov.x = pack2(y0, y1); ov.y = pack2(y2, y3);
;       if (do_store) *(uint2*)(MIX + row * 2048 + 1280 + e * 64 + pcol) = ov;
;       float ss = y0 * y0 + y1 * y1 + y2 * y2 + y3 * y3;
;       ss += __shfl_xor(ss, 16);
;       ss += __shfl_xor(ss, 32);
;       if (quad == 0) ssq_s[w * 64 + q] = ss;
;     }
.LBB0_545:
	s_or_b64 exec, exec, s[6:7]
	s_waitcnt vmcnt(6)
	v_lshlrev_b32_e32 v116, 16, v166
	s_waitcnt vmcnt(5)
	v_lshlrev_b32_e32 v118, 16, v168
	s_waitcnt lgkmcnt(0)
	v_and_b32_e32 v117, 0xffff0000, v166
	v_and_b32_e32 v119, 0xffff0000, v168
	v_mul_f32_e32 v120, 0xbfb8aa3b, v118
	v_pk_fma_f32 v[112:113], v[128:129], v[116:117], v[112:113]
	v_mul_f32_e32 v116, 0xbfb8aa3b, v119
	v_exp_f32_e32 v120, v120
	v_exp_f32_e32 v116, v116
	v_mov_b32_e32 v165, v161
	v_add_f32_e32 v120, 1.0, v120
	v_add_f32_e32 v116, 1.0, v116
	v_rcp_f32_e32 v120, v120
	v_rcp_f32_e32 v121, v116
	s_nop 0
	v_pk_mul_f32 v[116:117], v[120:121], v[118:119]
	s_nop 0
	v_pk_mul_f32 v[112:113], v[116:117], v[112:113]
	v_lshlrev_b32_e32 v116, 16, v167
	v_lshlrev_b32_e32 v118, 16, v169
	v_and_b32_e32 v117, 0xffff0000, v167
	v_and_b32_e32 v119, 0xffff0000, v169
	v_mul_f32_e32 v120, 0xbfb8aa3b, v118
	v_pk_fma_f32 v[114:115], v[128:129], v[116:117], v[114:115]
	v_mul_f32_e32 v116, 0xbfb8aa3b, v119
	v_exp_f32_e32 v120, v120
	v_exp_f32_e32 v116, v116
	v_add_f32_e32 v120, 1.0, v120
	v_add_f32_e32 v116, 1.0, v116
	v_rcp_f32_e32 v120, v120
	v_rcp_f32_e32 v121, v116
	s_nop 0
	v_pk_mul_f32 v[116:117], v[120:121], v[118:119]
	s_nop 0
	v_pk_mul_f32 v[114:115], v[116:117], v[114:115]
	v_cvt_pk_bf16_f32 v116, v112, v113
	v_pk_mul_f32 v[112:113], v[112:113], v[112:113]
	v_cvt_pk_bf16_f32 v117, v114, v115
	v_pk_mul_f32 v[114:115], v[114:115], v[114:115]
	v_add_f32_e32 v112, v112, v113
	v_add_f32_e32 v112, v114, v112
	v_add_f32_e32 v112, v115, v112
	v_mov_b32_e32 v113, v112
	s_nop 1
	v_permlane16_swap_b32_e32 v112, v113
	v_lshlrev_b64 v[118:119], 12, v[164:165]
	v_lshl_add_u64 v[118:119], s[94:95], 0, v[118:119]
	v_lshl_add_u64 v[118:119], v[118:119], 0, s[2:3]
	v_lshl_add_u64 v[118:119], v[134:135], 1, v[118:119]
	s_waitcnt lgkmcnt(0)
	v_add_f32_e32 v112, v112, v113
	v_mov_b32_e32 v113, v112
	s_nop 1
	v_permlane32_swap_b32_e32 v112, v113
	v_add_co_u32_e32 v118, vcc, s14, v118
	s_nop 1
	v_addc_co_u32_e32 v119, vcc, 0, v119, vcc
	global_store_dwordx2 v[118:119], v[116:117], off offset:2560
	s_and_saveexec_b64 s[6:7], s[38:39]
	s_cbranch_execz .LBB0_547
	s_waitcnt lgkmcnt(0)
	v_add_f32_e32 v112, v112, v113
	ds_write_b32 v240, v112 offset:64
.LBB0_547:
	s_or_b64 exec, exec, s[6:7]
	s_waitcnt vmcnt(5)
	v_lshlrev_b32_e32 v112, 16, v158
	s_waitcnt vmcnt(4)
	v_lshlrev_b32_e32 v114, 16, v156
	s_waitcnt lgkmcnt(0)
	v_and_b32_e32 v113, 0xffff0000, v158
	v_and_b32_e32 v115, 0xffff0000, v156
	v_mul_f32_e32 v116, 0xbfb8aa3b, v114
	v_pk_fma_f32 v[108:109], v[128:129], v[112:113], v[108:109]
	v_mul_f32_e32 v112, 0xbfb8aa3b, v115
	v_exp_f32_e32 v116, v116
	v_exp_f32_e32 v112, v112
	v_mov_b32_e32 v155, v161
	v_add_f32_e32 v116, 1.0, v116
	v_add_f32_e32 v112, 1.0, v112
	v_rcp_f32_e32 v116, v116
	v_rcp_f32_e32 v117, v112
	s_nop 0
	v_pk_mul_f32 v[112:113], v[116:117], v[114:115]
	s_nop 0
	v_pk_mul_f32 v[108:109], v[112:113], v[108:109]
	v_lshlrev_b32_e32 v112, 16, v159
	v_lshlrev_b32_e32 v114, 16, v157
	v_and_b32_e32 v113, 0xffff0000, v159
	v_and_b32_e32 v115, 0xffff0000, v157
	v_mul_f32_e32 v116, 0xbfb8aa3b, v114
	v_pk_fma_f32 v[110:111], v[128:129], v[112:113], v[110:111]
	v_mul_f32_e32 v112, 0xbfb8aa3b, v115
	v_exp_f32_e32 v116, v116
	v_exp_f32_e32 v112, v112
	v_add_f32_e32 v116, 1.0, v116
	v_add_f32_e32 v112, 1.0, v112
	v_rcp_f32_e32 v116, v116
	v_rcp_f32_e32 v117, v112
	s_nop 0
	v_pk_mul_f32 v[112:113], v[116:117], v[114:115]
	s_nop 0
	v_pk_mul_f32 v[110:111], v[112:113], v[110:111]
	v_cvt_pk_bf16_f32 v112, v108, v109
	v_pk_mul_f32 v[108:109], v[108:109], v[108:109]
	v_cvt_pk_bf16_f32 v113, v110, v111
	v_pk_mul_f32 v[110:111], v[110:111], v[110:111]
	v_add_f32_e32 v108, v108, v109
	v_add_f32_e32 v108, v110, v108
	v_add_f32_e32 v108, v111, v108
	v_mov_b32_e32 v109, v108
	s_nop 1
	v_permlane16_swap_b32_e32 v108, v109
	v_lshlrev_b64 v[114:115], 12, v[154:155]
	v_lshl_add_u64 v[114:115], s[94:95], 0, v[114:115]
	v_lshl_add_u64 v[114:115], v[114:115], 0, s[2:3]
	v_lshl_add_u64 v[114:115], v[134:135], 1, v[114:115]
	s_waitcnt lgkmcnt(0)
	v_add_f32_e32 v108, v108, v109
	v_mov_b32_e32 v109, v108
	s_nop 1
	v_permlane32_swap_b32_e32 v108, v109
	v_add_co_u32_e32 v114, vcc, s14, v114
	s_nop 1
	v_addc_co_u32_e32 v115, vcc, 0, v115, vcc
	global_store_dwordx2 v[114:115], v[112:113], off offset:2560
	s_and_saveexec_b64 s[6:7], s[38:39]
	s_cbranch_execz .LBB0_549
	s_waitcnt lgkmcnt(0)
	v_add_f32_e32 v108, v108, v109
	ds_write_b32 v240, v108 offset:128
.LBB0_549:
	s_or_b64 exec, exec, s[6:7]
	s_waitcnt vmcnt(4)
	v_lshlrev_b32_e32 v108, 16, v150
	s_waitcnt vmcnt(3)
	v_lshlrev_b32_e32 v110, 16, v152
	s_waitcnt lgkmcnt(0)
	v_and_b32_e32 v109, 0xffff0000, v150
	v_and_b32_e32 v111, 0xffff0000, v152
	v_mul_f32_e32 v112, 0xbfb8aa3b, v110
	v_pk_fma_f32 v[104:105], v[128:129], v[108:109], v[104:105]
	v_mul_f32_e32 v108, 0xbfb8aa3b, v111
	v_exp_f32_e32 v112, v112
	v_exp_f32_e32 v108, v108
	v_mov_b32_e32 v149, v161
	v_add_f32_e32 v112, 1.0, v112
	v_add_f32_e32 v108, 1.0, v108
	v_rcp_f32_e32 v112, v112
	v_rcp_f32_e32 v113, v108
	s_nop 0
	v_pk_mul_f32 v[108:109], v[112:113], v[110:111]
	s_nop 0
	v_pk_mul_f32 v[104:105], v[108:109], v[104:105]
	v_lshlrev_b32_e32 v108, 16, v151
	v_lshlrev_b32_e32 v110, 16, v153
	v_and_b32_e32 v109, 0xffff0000, v151
	v_and_b32_e32 v111, 0xffff0000, v153
	v_mul_f32_e32 v112, 0xbfb8aa3b, v110
	v_pk_fma_f32 v[106:107], v[128:129], v[108:109], v[106:107]
	v_mul_f32_e32 v108, 0xbfb8aa3b, v111
	v_exp_f32_e32 v112, v112
	v_exp_f32_e32 v108, v108
	v_add_f32_e32 v112, 1.0, v112
	v_add_f32_e32 v108, 1.0, v108
	v_rcp_f32_e32 v112, v112
	v_rcp_f32_e32 v113, v108
	s_nop 0
	v_pk_mul_f32 v[108:109], v[112:113], v[110:111]
	s_nop 0
	v_pk_mul_f32 v[106:107], v[108:109], v[106:107]
	v_cvt_pk_bf16_f32 v108, v104, v105
	v_pk_mul_f32 v[104:105], v[104:105], v[104:105]
	v_cvt_pk_bf16_f32 v109, v106, v107
	v_pk_mul_f32 v[106:107], v[106:107], v[106:107]
	v_add_f32_e32 v104, v104, v105
	v_add_f32_e32 v104, v106, v104
	v_add_f32_e32 v104, v107, v104
	v_mov_b32_e32 v105, v104
	s_nop 1
	v_permlane16_swap_b32_e32 v104, v105
	v_lshlrev_b64 v[110:111], 12, v[148:149]
	v_lshl_add_u64 v[110:111], s[94:95], 0, v[110:111]
	v_lshl_add_u64 v[110:111], v[110:111], 0, s[2:3]
	v_lshl_add_u64 v[110:111], v[134:135], 1, v[110:111]
	s_waitcnt lgkmcnt(0)
	v_add_f32_e32 v104, v104, v105
	v_mov_b32_e32 v105, v104
	s_nop 1
	v_permlane32_swap_b32_e32 v104, v105
	v_add_co_u32_e32 v110, vcc, s14, v110
	s_nop 1
	v_addc_co_u32_e32 v111, vcc, 0, v111, vcc
	global_store_dwordx2 v[110:111], v[108:109], off offset:2560
	s_and_saveexec_b64 s[6:7], s[38:39]
	s_cbranch_execz .LBB0_551
	s_waitcnt lgkmcnt(0)
	v_add_f32_e32 v104, v104, v105
	ds_write_b32 v240, v104 offset:192

; DI f32x4 mfma16(bf16x8 a, bf16x8 b, f32x4 c) { return __builtin_amdgcn_mfma_f32_16x16x32_bf16(a, b, c, 0, 0, 0); }
; template <int PROBE, int SONLY, int CPS>
; DI void ssd_chunk_loop(const Params& p, int layer, int b, int e, int c0, f32x4 (&h)[8], float& dtot, bool write_final) {
;     ...
;         *(uint2*)(Ms + q * 72 + s0) = ov;
;       }
;     }
;     f32x4 y[4];
; #pragma unroll
;     for (int qt = 0; qt < 4; ++qt) y[qt] = (f32x4){0.f, 0.f, 0.f, 0.f};
;     if (!(PROBE & 4) && !SONLY)
; #pragma unroll
;     for (int kk = 0; kk < 4; ++kk) {
;       const bf16x8 hf = packfrag(h[2 * kk], h[2 * kk + 1]);
; #pragma unroll
;       for (int qt = 0; qt < 4; ++qt) y[qt] = mfma16(hf, ldfrag_perm(Cs, 136, qt * 16, kk * 32, lane), y[qt]);
;     }
;     if (!SONLY) {
; #pragma unroll
;     for (int qt = 0; qt < 4; ++qt) y[qt] *= __expf(acs_s[qt * 16 + l15]);
;     __syncthreads();
;     }
;     if (!(PROBE & 8) && !SONLY)
; #pragma unroll
;     for (int qt = 0; qt < 4; ++qt)
; #pragma unroll
;       for (int ks = 0; ks < 2; ++ks)
;         if (ks == 0 || qt >= 2) y[qt] = mfma16(ldfrag(Xt, 72, w * 16, ks * 32, lane), ldfrag(Ms, 72, qt * 16, ks * 32, lane), y[qt]);
;     if (!(PROBE & 8)) {
;       const float cd = __expf(acs_s[63]);
; #pragma unroll
;       for (int nt = 0; nt < 8; ++nt) h[nt] *= cd;
; #pragma unroll
;       for (int ks = 0; ks < 2; ++ks) {
;         const bf16x8 xf = ldfrag(Xt, 72, w * 16, ks * 32, lane);
; #pragma unroll
;         for (int nt = 0; nt < 8; ++nt) h[nt] = mfma16(ldfrag(Bt2, 72, nt * 16, ks * 32, lane), xf, h[nt]);
;       }
.LBB0_595:
	s_or_b64 exec, exec, s[6:7]
	v_cvt_pk_bf16_f32 v74, v88, v76
	v_cvt_pk_bf16_f32 v75, v72, v73
	ds_write_b64 v177, v[74:75] offset:62560
	ds_read2_b64 v[224:227], v215 offset1:4
	v_add_u32_e32 v119, 0x1000, v215
	ds_read2_b64 v[228:231], v119 offset0:32 offset1:36
	v_add_u32_e32 v125, 0x2000, v215
	ds_read2_b64 v[232:235], v125 offset0:64 offset1:68
	v_add_u32_e32 v131, 0x3000, v215
	ds_read2_b64 v[236:239], v131 offset0:96 offset1:100
	ds_read2_b64 v[240:243], v215 offset0:8 offset1:12
	ds_read2_b64 v[244:247], v119 offset0:40 offset1:44
	ds_read2_b64 v[248:251], v125 offset0:72 offset1:76
	v_cvt_pk_bf16_f32 v72, v0, v1
	v_cvt_pk_bf16_f32 v73, v2, v3
	v_cvt_pk_bf16_f32 v74, v4, v5
	v_cvt_pk_bf16_f32 v75, v6, v7
	s_nop 0
	s_nop 0
	s_nop 0
	s_nop 0
	s_nop 0
	s_waitcnt lgkmcnt(6)
	v_mfma_f32_16x16x32_bf16 v[76:79], v[72:75], v[224:227], 0
	ds_read2_b64 v[224:227], v131 offset0:104 offset1:108
	s_nop 0
	v_ashrrev_i32_e32 v137, 31, v136
	s_nop 0
	s_waitcnt lgkmcnt(6)
	v_mfma_f32_16x16x32_bf16 v[80:83], v[72:75], v[228:231], 0
	ds_read2_b64 v[228:231], v215 offset0:16 offset1:20
	s_nop 0
	s_waitcnt lgkmcnt(6)
	v_mfma_f32_16x16x32_bf16 v[84:87], v[72:75], v[232:235], 0
	ds_read2_b64 v[232:235], v119 offset0:48 offset1:52
	s_nop 0
	s_waitcnt lgkmcnt(6)
	v_mfma_f32_16x16x32_bf16 v[72:75], v[72:75], v[236:239], 0
	ds_read2_b64 v[236:239], v125 offset0:80 offset1:84
	v_cvt_pk_bf16_f32 v88, v8, v9
	v_cvt_pk_bf16_f32 v89, v10, v11
	v_cvt_pk_bf16_f32 v90, v12, v13
	v_cvt_pk_bf16_f32 v91, v14, v15
	s_nop 0
	s_nop 0
	s_waitcnt lgkmcnt(6)
	v_mfma_f32_16x16x32_bf16 v[76:79], v[88:91], v[240:243], v[76:79]
	ds_read2_b64 v[240:243], v131 offset0:112 offset1:116
	s_nop 0
	s_nop 0
	s_waitcnt lgkmcnt(6)
	v_mfma_f32_16x16x32_bf16 v[80:83], v[88:91], v[244:247], v[80:83]
	ds_read2_b64 v[244:247], v215 offset0:24 offset1:28
	s_nop 0
	s_nop 0
	s_waitcnt lgkmcnt(6)
	v_mfma_f32_16x16x32_bf16 v[84:87], v[88:91], v[248:251], v[84:87]
	ds_read2_b64 v[248:251], v119 offset0:56 offset1:60
	s_nop 0
	s_nop 0
	s_waitcnt lgkmcnt(6)
	v_mfma_f32_16x16x32_bf16 v[72:75], v[88:91], v[224:227], v[72:75]
	ds_read2_b64 v[224:227], v125 offset0:88 offset1:92
	v_cvt_pk_bf16_f32 v88, v16, v17
	v_cvt_pk_bf16_f32 v89, v18, v19
	v_cvt_pk_bf16_f32 v90, v20, v21
	v_cvt_pk_bf16_f32 v91, v22, v23
	s_nop 0
	s_nop 0
	s_waitcnt lgkmcnt(6)
	v_mfma_f32_16x16x32_bf16 v[76:79], v[88:91], v[228:231], v[76:79]
	s_nop 0
	s_nop 0
	s_waitcnt lgkmcnt(5)
	v_mfma_f32_16x16x32_bf16 v[80:83], v[88:91], v[232:235], v[80:83]
	s_nop 0
	s_nop 0
	s_waitcnt lgkmcnt(4)
	v_mfma_f32_16x16x32_bf16 v[84:87], v[88:91], v[236:239], v[84:87]
	s_nop 0
	s_nop 0
	s_waitcnt lgkmcnt(3)
	v_mfma_f32_16x16x32_bf16 v[72:75], v[88:91], v[240:243], v[72:75]
	v_cvt_pk_bf16_f32 v88, v24, v25
	v_cvt_pk_bf16_f32 v89, v26, v27
	v_cvt_pk_bf16_f32 v90, v28, v29
	v_cvt_pk_bf16_f32 v91, v30, v31
	s_nop 0
	s_nop 0
	s_waitcnt lgkmcnt(2)
	v_mfma_f32_16x16x32_bf16 v[76:79], v[88:91], v[244:247], v[76:79]
	s_nop 0
	v_mov_b32_e32 v119, s20
	s_nop 0
	s_waitcnt lgkmcnt(1)
	v_mfma_f32_16x16x32_bf16 v[80:83], v[88:91], v[248:251], v[80:83]
	s_nop 0
	s_nop 0
	s_waitcnt lgkmcnt(0)
	v_mfma_f32_16x16x32_bf16 v[84:87], v[88:91], v[224:227], v[84:87]
	ds_read2_b64 v[92:95], v131 offset0:120 offset1:124
	s_nop 0
	s_waitcnt lgkmcnt(0)
	v_mfma_f32_16x16x32_bf16 v[72:75], v[88:91], v[92:95], v[72:75]
	ds_read2_b32 v[88:89], v157 offset1:16
	ds_read2_b32 v[90:91], v157 offset0:32 offset1:48
	s_waitcnt lgkmcnt(0)
	s_waitcnt lgkmcnt(0)
	s_barrier
	ds_read_b128 v[224:227], v158 offset:53248
	ds_read_b128 v[228:231], v216 offset:62464
	ds_read_b128 v[232:235], v216 offset:64768
	ds_read_b128 v[236:239], v217 offset:62464
	ds_read_b128 v[240:243], v217 offset:62528
	ds_read_b32 v244, v119
	ds_read_b128 v[248:251], v217 offset:64768
	v_mul_f32_e32 v88, 0x3fb8aa3b, v88
	v_exp_f32_e32 v88, v88
	v_mul_f32_e32 v91, 0x3fb8aa3b, v91
	v_exp_f32_e32 v92, v91
	v_pk_mul_f32 v[78:79], v[78:79], v[88:89] op_sel_hi:[1,0]
	v_pk_mul_f32 v[76:77], v[76:77], v[88:89] op_sel_hi:[1,0]
	v_mul_f32_e32 v88, 0x3fb8aa3b, v89
	v_exp_f32_e32 v88, v88
	v_pk_mul_f32 v[74:75], v[74:75], v[92:93] op_sel_hi:[1,0]
	v_pk_mul_f32 v[72:73], v[72:73], v[92:93] op_sel_hi:[1,0]
	v_pk_mul_f32 v[82:83], v[82:83], v[88:89] op_sel_hi:[1,0]
	v_pk_mul_f32 v[80:81], v[80:81], v[88:89] op_sel_hi:[1,0]
	v_mul_f32_e32 v88, 0x3fb8aa3b, v90
	v_exp_f32_e32 v88, v88
	s_nop 0
	v_pk_mul_f32 v[90:91], v[86:87], v[88:89] op_sel_hi:[1,0]
	v_pk_mul_f32 v[88:89], v[84:85], v[88:89] op_sel_hi:[1,0]
	s_nop 0
	s_nop 0
	s_nop 0
	s_waitcnt lgkmcnt(5)
	v_mfma_f32_16x16x32_bf16 v[84:87], v[224:227], v[228:231], v[76:79]
	ds_read_b128 v[228:231], v216 offset:34816
	s_nop 2
	s_nop 0
	s_nop 0
	s_waitcnt lgkmcnt(5)
	v_mfma_f32_16x16x32_bf16 v[80:83], v[224:227], v[232:235], v[80:83]
	ds_read_b128 v[232:235], v216 offset:37120
	s_nop 0
	s_nop 0
	s_waitcnt lgkmcnt(5)
	v_mfma_f32_16x16x32_bf16 v[76:79], v[224:227], v[236:239], v[88:91]
	ds_read_b128 v[236:239], v216 offset:39424
	s_nop 2
	ds_read_b128 v[88:91], v158 offset:53312
	s_nop 0
	s_nop 0
	s_nop 0
	s_waitcnt lgkmcnt(5)
	v_mul_f32_e32 v119, 0x3fb8aa3b, v244
	ds_read_b128 v[244:247], v216 offset:41728
	s_waitcnt lgkmcnt(1)
	v_mfma_f32_16x16x32_bf16 v[76:79], v[88:91], v[240:243], v[76:79]
	ds_read_b128 v[240:243], v216 offset:44032
	s_nop 0
	s_nop 0
	v_mfma_f32_16x16x32_bf16 v[72:75], v[224:227], v[248:251], v[72:75]
	ds_read_b128 v[248:251], v216 offset:46336
	ds_read_b128 v[218:221], v217 offset:64832
	s_nop 0
	s_waitcnt lgkmcnt(0)
; DI unsigned pack2(float a, float b) { fl2_t v = {a, b}; return __builtin_bit_cast(unsigned, __builtin_convertvector(v, bf2_t)); }
; DI float bflo(unsigned u) { return __uint_as_float(u << 16); }
; DI float bfhi(unsigned u) { return __uint_as_float(u & 0xffff0000u); }
; DI f32x4 mfma16(bf16x8 a, bf16x8 b, f32x4 c) { return __builtin_amdgcn_mfma_f32_16x16x32_bf16(a, b, c, 0, 0, 0); }
; DI float silu_f(float x) { return x * __builtin_amdgcn_rcpf(1.f + __expf(-x)); }
; template <int PROBE, int SONLY, int CPS>
; DI void ssd_chunk_loop(const Params& p, int layer, int b, int e, int c0, f32x4 (&h)[8], float& dtot, bool write_final) {
;     ...
;     if (!(PROBE & 8)) {
;       const float cd = __expf(acs_s[63]);
; #pragma unroll
;       for (int nt = 0; nt < 8; ++nt) h[nt] *= cd;
; #pragma unroll
;       for (int ks = 0; ks < 2; ++ks) {
;         const bf16x8 xf = ldfrag(Xt, 72, w * 16, ks * 32, lane);
; #pragma unroll
;         for (int nt = 0; nt < 8; ++nt) h[nt] = mfma16(ldfrag(Bt2, 72, nt * 16, ks * 32, lane), xf, h[nt]);
;       }
;     }
;     if (!SONLY)
; #pragma unroll
;     for (int qt = 0; qt < 4; ++qt) {
;       const int q = qt * 16 + l15;
;       const size_t row = (size_t)(base + q);
;       const int pcol = w * 16 + quad * 4;
;       const uint2 xv = dx[qt];
;       const uint2 zv = dz[qt];
;       const float y0 = (y[qt][0] + Dv * bflo(xv.x)) * silu_f(bflo(zv.x));
;       const float y1 = (y[qt][1] + Dv * bfhi(xv.x)) * silu_f(bfhi(zv.x));
;       const float y2 = (y[qt][2] + Dv * bflo(xv.y)) * silu_f(bflo(zv.y));
;       const float y3 = (y[qt][3] + Dv * bfhi(xv.y)) * silu_f(bfhi(zv.y));
;       uint2 ov; ov.x = pack2(y0, y1); ov.y = pack2(y2, y3);
;       if (do_store) *(uint2*)(MIX + row * 2048 + 1280 + e * 64 + pcol) = ov;
;       float ss = y0 * y0 + y1 * y1 + y2 * y2 + y3 * y3;
;       ss += __shfl_xor(ss, 16);
;       ss += __shfl_xor(ss, 32);
;       if (quad == 0) ssq_s[w * 64 + q] = ss;
;     }
	v_mfma_f32_16x16x32_bf16 v[72:75], v[88:91], v[218:221], v[72:75]
	v_exp_f32_e32 v218, v119
	s_nop 0
	v_pk_mul_f32 v[2:3], v[2:3], v[218:219] op_sel_hi:[1,0]
	v_pk_mul_f32 v[0:1], v[0:1], v[218:219] op_sel_hi:[1,0]
	v_pk_mul_f32 v[6:7], v[6:7], v[218:219] op_sel_hi:[1,0]
	v_pk_mul_f32 v[4:5], v[4:5], v[218:219] op_sel_hi:[1,0]
	v_pk_mul_f32 v[10:11], v[10:11], v[218:219] op_sel_hi:[1,0]
	v_pk_mul_f32 v[8:9], v[8:9], v[218:219] op_sel_hi:[1,0]
	v_pk_mul_f32 v[14:15], v[14:15], v[218:219] op_sel_hi:[1,0]
	v_pk_mul_f32 v[12:13], v[12:13], v[218:219] op_sel_hi:[1,0]
	v_pk_mul_f32 v[18:19], v[18:19], v[218:219] op_sel_hi:[1,0]
	v_pk_mul_f32 v[16:17], v[16:17], v[218:219] op_sel_hi:[1,0]
	v_pk_mul_f32 v[22:23], v[22:23], v[218:219] op_sel_hi:[1,0]
	v_pk_mul_f32 v[20:21], v[20:21], v[218:219] op_sel_hi:[1,0]
	v_pk_mul_f32 v[26:27], v[26:27], v[218:219] op_sel_hi:[1,0]
	v_pk_mul_f32 v[24:25], v[24:25], v[218:219] op_sel_hi:[1,0]
	v_pk_mul_f32 v[30:31], v[30:31], v[218:219] op_sel_hi:[1,0]
	v_pk_mul_f32 v[28:29], v[28:29], v[218:219] op_sel_hi:[1,0]
	s_nop 0
	s_nop 0
	v_mfma_f32_16x16x32_bf16 v[0:3], v[228:231], v[224:227], v[0:3]
	ds_read_b128 v[228:231], v216 offset:48640
	s_nop 0
	s_nop 0
	v_mfma_f32_16x16x32_bf16 v[4:7], v[232:235], v[224:227], v[4:7]
	ds_read_b128 v[232:235], v216 offset:34880
	s_nop 0
	s_nop 0
	v_mfma_f32_16x16x32_bf16 v[8:11], v[236:239], v[224:227], v[8:11]
	ds_read_b128 v[236:239], v216 offset:37184
	s_nop 0
	s_nop 0
	v_mfma_f32_16x16x32_bf16 v[12:15], v[244:247], v[224:227], v[12:15]
	ds_read_b128 v[244:247], v216 offset:39488
	s_nop 0
	s_nop 0
	v_mfma_f32_16x16x32_bf16 v[16:19], v[240:243], v[224:227], v[16:19]
	ds_read_b128 v[240:243], v216 offset:41792
	s_nop 0
	s_nop 0
	v_mfma_f32_16x16x32_bf16 v[20:23], v[248:251], v[224:227], v[20:23]
	ds_read_b128 v[248:251], v216 offset:44096
	s_nop 0
	s_nop 0
	s_waitcnt lgkmcnt(5)
	v_mfma_f32_16x16x32_bf16 v[24:27], v[228:231], v[224:227], v[24:27]
	ds_read_b128 v[228:231], v216 offset:46400
	ds_read_b128 v[218:221], v216 offset:50944
	s_nop 0
	s_waitcnt lgkmcnt(0)
	v_mfma_f32_16x16x32_bf16 v[28:31], v[218:221], v[224:227], v[28:31]
	ds_read_b128 v[224:227], v216 offset:48704
	s_nop 0
	s_nop 0
	v_mfma_f32_16x16x32_bf16 v[0:3], v[232:235], v[88:91], v[0:3]
	s_nop 0
	s_nop 0
	v_mfma_f32_16x16x32_bf16 v[4:7], v[236:239], v[88:91], v[4:7]
	s_nop 0
	s_nop 0
	v_mfma_f32_16x16x32_bf16 v[8:11], v[244:247], v[88:91], v[8:11]
	s_nop 0
	s_nop 0
	v_mfma_f32_16x16x32_bf16 v[12:15], v[240:243], v[88:91], v[12:15]
	s_nop 0
	s_nop 0
	v_mfma_f32_16x16x32_bf16 v[16:19], v[248:251], v[88:91], v[16:19]
	s_nop 0
	s_nop 0
	v_mfma_f32_16x16x32_bf16 v[20:23], v[228:231], v[88:91], v[20:23]
	s_nop 0
	s_nop 0
	s_waitcnt lgkmcnt(0)
	v_mfma_f32_16x16x32_bf16 v[24:27], v[224:227], v[88:91], v[24:27]
	ds_read_b128 v[92:95], v216 offset:51008
	s_nop 0
	s_waitcnt lgkmcnt(0)
	v_mfma_f32_16x16x32_bf16 v[28:31], v[92:95], v[88:91], v[28:31]
	s_waitcnt vmcnt(7)
	v_lshlrev_b32_e32 v88, 16, v140
	s_waitcnt vmcnt(6)
	v_lshlrev_b32_e32 v90, 16, v138
	v_and_b32_e32 v89, 0xffff0000, v140
	v_and_b32_e32 v91, 0xffff0000, v138
	v_mul_f32_e32 v92, 0xbfb8aa3b, v90
	v_pk_fma_f32 v[84:85], v[96:97], v[88:89], v[84:85]
	v_mul_f32_e32 v88, 0xbfb8aa3b, v91
	v_exp_f32_e32 v92, v92
	v_exp_f32_e32 v88, v88
	v_add_f32_e32 v92, 1.0, v92
	v_add_f32_e32 v88, 1.0, v88
	v_rcp_f32_e32 v92, v92
	v_rcp_f32_e32 v93, v88
	s_nop 0
	v_pk_mul_f32 v[88:89], v[92:93], v[90:91]
	s_nop 0
	v_pk_mul_f32 v[84:85], v[88:89], v[84:85]
	v_lshlrev_b32_e32 v88, 16, v141
	v_lshlrev_b32_e32 v90, 16, v139
	v_and_b32_e32 v89, 0xffff0000, v141
	v_and_b32_e32 v91, 0xffff0000, v139
	v_mul_f32_e32 v92, 0xbfb8aa3b, v90
	v_pk_fma_f32 v[86:87], v[96:97], v[88:89], v[86:87]
	v_mul_f32_e32 v88, 0xbfb8aa3b, v91
	v_exp_f32_e32 v92, v92
	v_exp_f32_e32 v88, v88
	v_add_f32_e32 v92, 1.0, v92
	v_add_f32_e32 v88, 1.0, v88
	v_rcp_f32_e32 v92, v92
	v_rcp_f32_e32 v93, v88
	s_nop 0
	v_pk_mul_f32 v[88:89], v[92:93], v[90:91]
	s_nop 0
	v_pk_mul_f32 v[86:87], v[88:89], v[86:87]
	v_cvt_pk_bf16_f32 v88, v84, v85
	v_pk_mul_f32 v[84:85], v[84:85], v[84:85]
	v_cvt_pk_bf16_f32 v89, v86, v87
	v_pk_mul_f32 v[86:87], v[86:87], v[86:87]
	v_add_f32_e32 v84, v84, v85
	v_add_f32_e32 v84, v86, v84
	v_add_f32_e32 v84, v87, v84
	v_mov_b32_e32 v85, v84
	s_nop 1
	v_permlane16_swap_b32_e32 v84, v85
	v_lshlrev_b64 v[90:91], 12, v[136:137]
	v_lshl_add_u64 v[90:91], s[94:95], 0, v[90:91]
	v_lshl_add_u64 v[90:91], s[0:1], 1, v[90:91]
	v_lshl_add_u64 v[90:91], v[102:103], 1, v[90:91]
	s_waitcnt lgkmcnt(0)
	v_add_f32_e32 v84, v84, v85
	v_mov_b32_e32 v85, v84
	s_nop 1
	v_permlane32_swap_b32_e32 v84, v85
	v_add_co_u32_e32 v90, vcc, s14, v90
	s_nop 1
	v_addc_co_u32_e32 v91, vcc, 0, v91, vcc
	global_store_dwordx2 v[90:91], v[88:89], off offset:2560
	s_and_saveexec_b64 s[6:7], s[38:39]
	s_cbranch_execz .LBB0_597
	s_waitcnt lgkmcnt(0)
	v_add_f32_e32 v84, v84, v85
	ds_write_b32 v212, v84
; DI unsigned pack2(float a, float b) { fl2_t v = {a, b}; return __builtin_bit_cast(unsigned, __builtin_convertvector(v, bf2_t)); }
; DI float bflo(unsigned u) { return __uint_as_float(u << 16); }
; DI float bfhi(unsigned u) { return __uint_as_float(u & 0xffff0000u); }
; DI float silu_f(float x) { return x * __builtin_amdgcn_rcpf(1.f + __expf(-x)); }
; template <int PROBE, int SONLY, int CPS>
; DI void ssd_chunk_loop(const Params& p, int layer, int b, int e, int c0, f32x4 (&h)[8], float& dtot, bool write_final) {
;     ...
;     for (int qt = 0; qt < 4; ++qt) {
;       const int q = qt * 16 + l15;
;       const size_t row = (size_t)(base + q);
;       const int pcol = w * 16 + quad * 4;
;       const uint2 xv = dx[qt];
;       const uint2 zv = dz[qt];
;       const float y0 = (y[qt][0] + Dv * bflo(xv.x)) * silu_f(bflo(zv.x));
;       const float y1 = (y[qt][1] + Dv * bfhi(xv.x)) * silu_f(bfhi(zv.x));
;       const float y2 = (y[qt][2] + Dv * bflo(xv.y)) * silu_f(bflo(zv.y));
;       const float y3 = (y[qt][3] + Dv * bfhi(xv.y)) * silu_f(bfhi(zv.y));
;       uint2 ov; ov.x = pack2(y0, y1); ov.y = pack2(y2, y3);
;       if (do_store) *(uint2*)(MIX + row * 2048 + 1280 + e * 64 + pcol) = ov;
;       float ss = y0 * y0 + y1 * y1 + y2 * y2 + y3 * y3;
;       ss += __shfl_xor(ss, 16);
;       ss += __shfl_xor(ss, 32);
;       if (quad == 0) ssq_s[w * 64 + q] = ss;
;     }
.LBB0_597:
	s_or_b64 exec, exec, s[6:7]
	s_waitcnt vmcnt(6)
	v_lshlrev_b32_e32 v84, 16, v132
	s_waitcnt vmcnt(5)
	v_lshlrev_b32_e32 v86, 16, v134
	s_waitcnt lgkmcnt(0)
	v_and_b32_e32 v85, 0xffff0000, v132
	v_and_b32_e32 v87, 0xffff0000, v134
	v_mul_f32_e32 v88, 0xbfb8aa3b, v86
	v_pk_fma_f32 v[80:81], v[96:97], v[84:85], v[80:81]
	v_mul_f32_e32 v84, 0xbfb8aa3b, v87
	v_exp_f32_e32 v88, v88
	v_exp_f32_e32 v84, v84
	v_ashrrev_i32_e32 v131, 31, v130
	v_add_f32_e32 v88, 1.0, v88
	v_add_f32_e32 v84, 1.0, v84
	v_rcp_f32_e32 v88, v88
	v_rcp_f32_e32 v89, v84
	s_nop 0
	v_pk_mul_f32 v[84:85], v[88:89], v[86:87]
	s_nop 0
	v_pk_mul_f32 v[80:81], v[84:85], v[80:81]
	v_lshlrev_b32_e32 v84, 16, v133
	v_lshlrev_b32_e32 v86, 16, v135
	v_and_b32_e32 v85, 0xffff0000, v133
	v_and_b32_e32 v87, 0xffff0000, v135
	v_mul_f32_e32 v88, 0xbfb8aa3b, v86
	v_pk_fma_f32 v[82:83], v[96:97], v[84:85], v[82:83]
	v_mul_f32_e32 v84, 0xbfb8aa3b, v87
	v_exp_f32_e32 v88, v88
	v_exp_f32_e32 v84, v84
	v_add_f32_e32 v88, 1.0, v88
	v_add_f32_e32 v84, 1.0, v84
	v_rcp_f32_e32 v88, v88
	v_rcp_f32_e32 v89, v84
	s_nop 0
	v_pk_mul_f32 v[84:85], v[88:89], v[86:87]
	s_nop 0
	v_pk_mul_f32 v[82:83], v[84:85], v[82:83]
	v_cvt_pk_bf16_f32 v84, v80, v81
	v_pk_mul_f32 v[80:81], v[80:81], v[80:81]
	v_cvt_pk_bf16_f32 v85, v82, v83
	v_pk_mul_f32 v[82:83], v[82:83], v[82:83]
	v_add_f32_e32 v80, v80, v81
	v_add_f32_e32 v80, v82, v80
	v_add_f32_e32 v80, v83, v80
	v_mov_b32_e32 v81, v80
	s_nop 1
	v_permlane16_swap_b32_e32 v80, v81
	v_lshlrev_b64 v[86:87], 12, v[130:131]
	v_lshl_add_u64 v[86:87], s[94:95], 0, v[86:87]
	v_lshl_add_u64 v[86:87], s[0:1], 1, v[86:87]
	v_lshl_add_u64 v[86:87], v[102:103], 1, v[86:87]
	s_waitcnt lgkmcnt(0)
	v_add_f32_e32 v80, v80, v81
	v_mov_b32_e32 v81, v80
	s_nop 1
	v_permlane32_swap_b32_e32 v80, v81
	v_add_co_u32_e32 v86, vcc, s14, v86
	s_nop 1
	v_addc_co_u32_e32 v87, vcc, 0, v87, vcc
	global_store_dwordx2 v[86:87], v[84:85], off offset:2560
	s_and_saveexec_b64 s[6:7], s[38:39]
	s_cbranch_execz .LBB0_599
	s_waitcnt lgkmcnt(0)
	v_add_f32_e32 v80, v80, v81
	ds_write_b32 v212, v80 offset:64
.LBB0_599:
	s_or_b64 exec, exec, s[6:7]
	s_waitcnt vmcnt(5)
	v_lshlrev_b32_e32 v80, 16, v128
	s_waitcnt vmcnt(4)
	v_lshlrev_b32_e32 v82, 16, v126
	s_waitcnt lgkmcnt(0)
	v_and_b32_e32 v81, 0xffff0000, v128
	v_and_b32_e32 v83, 0xffff0000, v126
	v_mul_f32_e32 v84, 0xbfb8aa3b, v82
	v_pk_fma_f32 v[76:77], v[96:97], v[80:81], v[76:77]
	v_mul_f32_e32 v80, 0xbfb8aa3b, v83
	v_exp_f32_e32 v84, v84
	v_exp_f32_e32 v80, v80
	v_ashrrev_i32_e32 v125, 31, v124
	v_add_f32_e32 v84, 1.0, v84
	v_add_f32_e32 v80, 1.0, v80
	v_rcp_f32_e32 v84, v84
	v_rcp_f32_e32 v85, v80
	s_nop 0
	v_pk_mul_f32 v[80:81], v[84:85], v[82:83]
	s_nop 0
	v_pk_mul_f32 v[76:77], v[80:81], v[76:77]
	v_lshlrev_b32_e32 v80, 16, v129
	v_lshlrev_b32_e32 v82, 16, v127
	v_and_b32_e32 v81, 0xffff0000, v129
	v_and_b32_e32 v83, 0xffff0000, v127
	v_mul_f32_e32 v84, 0xbfb8aa3b, v82
	v_pk_fma_f32 v[78:79], v[96:97], v[80:81], v[78:79]
	v_mul_f32_e32 v80, 0xbfb8aa3b, v83
	v_exp_f32_e32 v84, v84
	v_exp_f32_e32 v80, v80
	v_add_f32_e32 v84, 1.0, v84
	v_add_f32_e32 v80, 1.0, v80
	v_rcp_f32_e32 v84, v84
	v_rcp_f32_e32 v85, v80
	s_nop 0
	v_pk_mul_f32 v[80:81], v[84:85], v[82:83]
	s_nop 0
	v_pk_mul_f32 v[78:79], v[80:81], v[78:79]
	v_cvt_pk_bf16_f32 v80, v76, v77
	v_pk_mul_f32 v[76:77], v[76:77], v[76:77]
	v_cvt_pk_bf16_f32 v81, v78, v79
	v_pk_mul_f32 v[78:79], v[78:79], v[78:79]
	v_add_f32_e32 v76, v76, v77
	v_add_f32_e32 v76, v78, v76
	v_add_f32_e32 v76, v79, v76
	v_mov_b32_e32 v77, v76
	s_nop 1
	v_permlane16_swap_b32_e32 v76, v77
	v_lshlrev_b64 v[82:83], 12, v[124:125]
	v_lshl_add_u64 v[82:83], s[94:95], 0, v[82:83]
	v_lshl_add_u64 v[82:83], s[0:1], 1, v[82:83]
	v_lshl_add_u64 v[82:83], v[102:103], 1, v[82:83]
	s_waitcnt lgkmcnt(0)
	v_add_f32_e32 v76, v76, v77
	v_mov_b32_e32 v77, v76
	s_nop 1
	v_permlane32_swap_b32_e32 v76, v77
	v_add_co_u32_e32 v82, vcc, s14, v82
	s_nop 1
	v_addc_co_u32_e32 v83, vcc, 0, v83, vcc
	global_store_dwordx2 v[82:83], v[80:81], off offset:2560
	s_and_saveexec_b64 s[6:7], s[38:39]
	s_cbranch_execz .LBB0_601
	s_waitcnt lgkmcnt(0)
	v_add_f32_e32 v76, v76, v77
	ds_write_b32 v212, v76 offset:128
.LBB0_601:
	s_or_b64 exec, exec, s[6:7]
	s_waitcnt vmcnt(4)
	v_lshlrev_b32_e32 v76, 16, v120
	s_waitcnt vmcnt(3)
	v_lshlrev_b32_e32 v78, 16, v122
	s_waitcnt lgkmcnt(0)
	v_and_b32_e32 v77, 0xffff0000, v120
	v_and_b32_e32 v79, 0xffff0000, v122
	v_mul_f32_e32 v80, 0xbfb8aa3b, v78
	v_pk_fma_f32 v[72:73], v[96:97], v[76:77], v[72:73]
	v_mul_f32_e32 v76, 0xbfb8aa3b, v79
	v_exp_f32_e32 v80, v80
	v_exp_f32_e32 v76, v76
	v_ashrrev_i32_e32 v119, 31, v118
	v_add_f32_e32 v80, 1.0, v80
	v_add_f32_e32 v76, 1.0, v76
	v_rcp_f32_e32 v80, v80
	v_rcp_f32_e32 v81, v76
	s_nop 0
	v_pk_mul_f32 v[76:77], v[80:81], v[78:79]
	s_nop 0
	v_pk_mul_f32 v[72:73], v[76:77], v[72:73]
	v_lshlrev_b32_e32 v76, 16, v121
	v_lshlrev_b32_e32 v78, 16, v123
	v_and_b32_e32 v77, 0xffff0000, v121
	v_and_b32_e32 v79, 0xffff0000, v123
	v_mul_f32_e32 v80, 0xbfb8aa3b, v78
	v_pk_fma_f32 v[74:75], v[96:97], v[76:77], v[74:75]
	v_mul_f32_e32 v76, 0xbfb8aa3b, v79
	v_exp_f32_e32 v80, v80
	v_exp_f32_e32 v76, v76
	v_add_f32_e32 v80, 1.0, v80
	v_add_f32_e32 v76, 1.0, v76
	v_rcp_f32_e32 v80, v80
	v_rcp_f32_e32 v81, v76
	s_nop 0
	v_pk_mul_f32 v[76:77], v[80:81], v[78:79]
	s_nop 0
	v_pk_mul_f32 v[74:75], v[76:77], v[74:75]
	v_cvt_pk_bf16_f32 v76, v72, v73
	v_pk_mul_f32 v[72:73], v[72:73], v[72:73]
	v_cvt_pk_bf16_f32 v77, v74, v75
	v_pk_mul_f32 v[74:75], v[74:75], v[74:75]
	v_add_f32_e32 v72, v72, v73
	v_add_f32_e32 v72, v74, v72
	v_add_f32_e32 v72, v75, v72
	v_mov_b32_e32 v73, v72
	s_nop 1
	v_permlane16_swap_b32_e32 v72, v73
	v_lshlrev_b64 v[78:79], 12, v[118:119]
	v_lshl_add_u64 v[78:79], s[94:95], 0, v[78:79]
	v_lshl_add_u64 v[78:79], s[0:1], 1, v[78:79]
	v_lshl_add_u64 v[78:79], v[102:103], 1, v[78:79]
	s_waitcnt lgkmcnt(0)
	v_add_f32_e32 v72, v72, v73
	v_mov_b32_e32 v73, v72
	s_nop 1
	v_permlane32_swap_b32_e32 v72, v73
	v_add_co_u32_e32 v78, vcc, s14, v78
	s_nop 1
	v_addc_co_u32_e32 v79, vcc, 0, v79, vcc
	global_store_dwordx2 v[78:79], v[76:77], off offset:2560
	s_and_saveexec_b64 s[6:7], s[38:39]
	s_cbranch_execz .LBB0_603
	s_waitcnt lgkmcnt(0)
	v_add_f32_e32 v72, v72, v73
	ds_write_b32 v212, v72 offset:192
